# P5/P6 quarter units: dedicated K loop, MFMAs software-pipelined by one K step into a second fragment register set (reads overlap the matrix work), same LDS-DMA schedule and barriers
# speedup vs baseline: 1.0073x; 1.0054x over previous
.LBB0_1132:
	s_andn2_b64 vcc, exec, s[26:27]
	s_cbranch_vccnz .Lq5_entry
	ds_read_b128 v[148:151], v214
	ds_read_b128 v[152:155], v214 offset:1024
	ds_read_b128 v[156:159], v214 offset:2048
	ds_read_b128 v[160:163], v214 offset:3072
	ds_read_b128 v[132:135], v215
	ds_read_b128 v[136:139], v215 offset:1024
	ds_read_b128 v[140:143], v215 offset:2048
	ds_read_b128 v[144:147], v215 offset:3072
	v_lshl_add_u64 v[2:3], s[34:35], 0, v[200:201]
	s_add_i32 m0, s48, 0xc000
	s_waitcnt lgkmcnt(0)
	ds_read_b128 v[188:191], v216
	ds_read_b128 v[192:195], v216 offset:1024
	ds_read_b128 v[180:183], v216 offset:2048
	ds_read_b128 v[184:187], v216 offset:3072
	ds_read_b128 v[172:175], v216 offset:4096
	ds_read_b128 v[176:179], v216 offset:5120
	ds_read_b128 v[164:167], v216 offset:6144
	ds_read_b128 v[168:171], v216 offset:7168
	global_load_lds_dwordx4 v[2:3], off
	v_lshl_add_u64 v[2:3], s[34:35], 0, v[202:203]
	s_add_i32 m0, s48, 0xe000
	s_nop 0
	global_load_lds_dwordx4 v[2:3], off
	s_waitcnt vmcnt(8)
	s_waitcnt lgkmcnt(0)
	s_barrier
	s_setprio 1
	s_waitcnt lgkmcnt(0)
	v_mfma_f32_16x16x32_bf16 v[128:131], v[148:151], v[188:191], v[128:131]
	v_mfma_f32_16x16x32_bf16 v[124:127], v[156:159], v[188:191], v[124:127]
	v_mfma_f32_16x16x32_bf16 v[120:123], v[148:151], v[180:183], v[120:123]
	v_mfma_f32_16x16x32_bf16 v[116:119], v[156:159], v[180:183], v[116:119]
	v_mfma_f32_16x16x32_bf16 v[104:107], v[148:151], v[172:175], v[104:107]
	v_mfma_f32_16x16x32_bf16 v[100:103], v[156:159], v[172:175], v[100:103]
	v_mfma_f32_16x16x32_bf16 v[88:91], v[148:151], v[164:167], v[88:91]
	v_mfma_f32_16x16x32_bf16 v[84:87], v[156:159], v[164:167], v[84:87]
	v_mfma_f32_16x16x32_bf16 v[128:131], v[152:155], v[192:195], v[128:131]
	v_mfma_f32_16x16x32_bf16 v[124:127], v[160:163], v[192:195], v[124:127]
	v_mfma_f32_16x16x32_bf16 v[120:123], v[152:155], v[184:187], v[120:123]
	v_mfma_f32_16x16x32_bf16 v[116:119], v[160:163], v[184:187], v[116:119]
	v_mfma_f32_16x16x32_bf16 v[104:107], v[152:155], v[176:179], v[104:107]
	v_mfma_f32_16x16x32_bf16 v[100:103], v[160:163], v[176:179], v[100:103]
	v_mfma_f32_16x16x32_bf16 v[88:91], v[152:155], v[168:171], v[88:91]
	v_mfma_f32_16x16x32_bf16 v[84:87], v[160:163], v[168:171], v[84:87]
	s_setprio 0
	v_cmp_ne_u32_e64 s[2:3], 1, v217
	s_andn2_b64 vcc, exec, s[26:27]
	s_cbranch_vccnz .LBB0_1134
	s_setprio 1
	v_mfma_f32_16x16x32_bf16 v[112:115], v[132:135], v[188:191], v[112:115]
	v_mfma_f32_16x16x32_bf16 v[108:111], v[140:143], v[188:191], v[108:111]
	v_mfma_f32_16x16x32_bf16 v[96:99], v[132:135], v[180:183], v[96:99]
	v_mfma_f32_16x16x32_bf16 v[92:95], v[140:143], v[180:183], v[92:95]
	v_mfma_f32_16x16x32_bf16 v[80:83], v[132:135], v[172:175], v[80:83]
	v_mfma_f32_16x16x32_bf16 v[76:79], v[140:143], v[172:175], v[76:79]
	v_mfma_f32_16x16x32_bf16 v[72:75], v[132:135], v[164:167], v[72:75]
	v_mfma_f32_16x16x32_bf16 v[68:71], v[140:143], v[164:167], v[68:71]
	v_mfma_f32_16x16x32_bf16 v[112:115], v[136:139], v[192:195], v[112:115]
	v_mfma_f32_16x16x32_bf16 v[108:111], v[144:147], v[192:195], v[108:111]
	v_mfma_f32_16x16x32_bf16 v[96:99], v[136:139], v[184:187], v[96:99]
	v_mfma_f32_16x16x32_bf16 v[92:95], v[144:147], v[184:187], v[92:95]
	v_mfma_f32_16x16x32_bf16 v[80:83], v[136:139], v[176:179], v[80:83]
	v_mfma_f32_16x16x32_bf16 v[76:79], v[144:147], v[176:179], v[76:79]
	v_mfma_f32_16x16x32_bf16 v[72:75], v[136:139], v[168:171], v[72:75]
	v_mfma_f32_16x16x32_bf16 v[68:71], v[144:147], v[168:171], v[68:71]
	s_setprio 0

.Lq5_entry:
	v_mov_b32_e32 v4, 0
	v_mov_b32_e32 v5, 0
	v_mov_b32_e32 v6, 0
	v_mov_b32_e32 v7, 0
	v_mov_b32_e32 v8, 0
	v_mov_b32_e32 v9, 0
	v_mov_b32_e32 v10, 0
	v_mov_b32_e32 v11, 0
	v_mov_b32_e32 v12, 0
	v_mov_b32_e32 v13, 0
	v_mov_b32_e32 v14, 0
	v_mov_b32_e32 v15, 0
	v_mov_b32_e32 v16, 0
	v_mov_b32_e32 v17, 0
	v_mov_b32_e32 v18, 0
	v_mov_b32_e32 v19, 0
	v_mov_b32_e32 v20, 0
	v_mov_b32_e32 v21, 0
	v_mov_b32_e32 v22, 0
	v_mov_b32_e32 v23, 0
	v_mov_b32_e32 v24, 0
	v_mov_b32_e32 v25, 0
	v_mov_b32_e32 v26, 0
	v_mov_b32_e32 v27, 0
	v_mov_b32_e32 v28, 0
	v_mov_b32_e32 v29, 0
	v_mov_b32_e32 v30, 0
	v_mov_b32_e32 v31, 0
	v_mov_b32_e32 v32, 0
	v_mov_b32_e32 v33, 0
	v_mov_b32_e32 v34, 0
	v_mov_b32_e32 v35, 0
	v_mov_b32_e32 v36, 0
	v_mov_b32_e32 v37, 0
	v_mov_b32_e32 v38, 0
	v_mov_b32_e32 v39, 0
	v_mov_b32_e32 v40, 0
	v_mov_b32_e32 v41, 0
	v_mov_b32_e32 v42, 0
	v_mov_b32_e32 v43, 0
	v_mov_b32_e32 v44, 0
	v_mov_b32_e32 v45, 0
	v_mov_b32_e32 v46, 0
	v_mov_b32_e32 v47, 0
	v_mov_b32_e32 v48, 0
	v_mov_b32_e32 v49, 0
	v_mov_b32_e32 v50, 0
	v_mov_b32_e32 v51, 0
	s_branch .Lq5_top

.Lq5_top:
	ds_read_b128 v[148:151], v214
	ds_read_b128 v[152:155], v214 offset:1024
	ds_read_b128 v[156:159], v214 offset:2048
	ds_read_b128 v[160:163], v214 offset:3072
	v_lshl_add_u64 v[2:3], s[34:35], 0, v[200:201]
	s_add_i32 m0, s48, 0xc000
	ds_read_b128 v[188:191], v216
	ds_read_b128 v[192:195], v216 offset:1024
	ds_read_b128 v[180:183], v216 offset:2048
	ds_read_b128 v[184:187], v216 offset:3072
	ds_read_b128 v[172:175], v216 offset:4096
	ds_read_b128 v[176:179], v216 offset:5120
	ds_read_b128 v[164:167], v216 offset:6144
	ds_read_b128 v[168:171], v216 offset:7168
	v_lshl_add_u64 v[2:3], s[34:35], 0, v[202:203]
	s_add_i32 m0, s48, 0xe000
	s_nop 0
	s_waitcnt vmcnt(4)
	s_barrier
	s_setprio 1
	v_mfma_f32_16x16x32_bf16 v[128:131], v[4:7], v[44:47], v[128:131]
	v_mfma_f32_16x16x32_bf16 v[124:127], v[12:15], v[44:47], v[124:127]
	v_mfma_f32_16x16x32_bf16 v[120:123], v[4:7], v[36:39], v[120:123]
	v_mfma_f32_16x16x32_bf16 v[116:119], v[12:15], v[36:39], v[116:119]
	v_mfma_f32_16x16x32_bf16 v[104:107], v[4:7], v[28:31], v[104:107]
	v_mfma_f32_16x16x32_bf16 v[100:103], v[12:15], v[28:31], v[100:103]
	v_mfma_f32_16x16x32_bf16 v[88:91], v[4:7], v[20:23], v[88:91]
	v_mfma_f32_16x16x32_bf16 v[84:87], v[12:15], v[20:23], v[84:87]
	v_mfma_f32_16x16x32_bf16 v[128:131], v[8:11], v[48:51], v[128:131]
	v_mfma_f32_16x16x32_bf16 v[124:127], v[16:19], v[48:51], v[124:127]
	v_mfma_f32_16x16x32_bf16 v[120:123], v[8:11], v[40:43], v[120:123]
	v_mfma_f32_16x16x32_bf16 v[116:119], v[16:19], v[40:43], v[116:119]
	v_mfma_f32_16x16x32_bf16 v[104:107], v[8:11], v[32:35], v[104:107]
	v_mfma_f32_16x16x32_bf16 v[100:103], v[16:19], v[32:35], v[100:103]
	v_mfma_f32_16x16x32_bf16 v[88:91], v[8:11], v[24:27], v[88:91]
	v_mfma_f32_16x16x32_bf16 v[84:87], v[16:19], v[24:27], v[84:87]
	s_setprio 0
	v_cmp_ne_u32_e64 s[2:3], 1, v217
	s_andn2_b64 vcc, exec, s[26:27]
	s_add_u32 s56, s34, 0xfff80080
	s_addc_u32 s57, s35, -1
	s_cmp_eq_u32 s77, 12
	s_cselect_b32 s59, s39, s57
	s_cselect_b32 s58, s38, s56
	s_cselect_b32 s57, s47, s41
	s_cselect_b32 s56, s46, s18
	s_waitcnt lgkmcnt(0)
	s_barrier
	s_mov_b32 m0, s49
	v_lshl_add_u64 v[2:3], s[56:57], 0, v[198:199]
	s_add_u32 s78, s56, 0x80000
	global_load_lds_dwordx4 v[2:3], off
	v_lshl_add_u64 v[204:205], s[56:57], 0, v[196:197]
	s_mov_b32 m0, s50
	s_addc_u32 s79, s57, 0
	global_load_lds_dwordx4 v[204:205], off
	v_lshl_add_u64 v[206:207], s[78:79], 0, v[198:199]
	s_mov_b32 m0, s51
	v_lshl_add_u64 v[208:209], s[58:59], 0, v[196:197]
	v_lshl_add_u64 v[206:207], s[78:79], 0, v[196:197]
	s_mov_b32 m0, s60
	s_and_b64 vcc, exec, s[2:3]
	v_lshl_add_u64 v[206:207], s[58:59], 0, v[198:199]
	s_mov_b32 m0, s48
	s_nop 0
	global_load_lds_dwordx4 v[206:207], off
	s_mov_b32 m0, s61
	s_nop 0
	global_load_lds_dwordx4 v[208:209], off
	s_waitcnt vmcnt(4)
	s_waitcnt lgkmcnt(0)
	s_barrier
	s_barrier
	v_add_u32_e32 v1, 0x18000, v213
	ds_read_b128 v[4:7], v1
	ds_read_b128 v[8:11], v1 offset:1024
	ds_read_b128 v[12:15], v1 offset:2048
	ds_read_b128 v[16:19], v1 offset:3072
	v_add_u32_e32 v1, 0x1c000, v213
	s_add_u32 s58, s58, 0x80000
	s_addc_u32 s59, s59, 0
	s_mov_b32 m0, s62
	v_lshl_add_u64 v[218:219], s[58:59], 0, v[198:199]
	ds_read_b128 v[44:47], v216 offset:32768
	ds_read_b128 v[48:51], v216 offset:33792
	ds_read_b128 v[36:39], v216 offset:34816
	ds_read_b128 v[40:43], v216 offset:35840
	ds_read_b128 v[28:31], v216 offset:36864
	ds_read_b128 v[32:35], v216 offset:37888
	ds_read_b128 v[20:23], v216 offset:38912
	ds_read_b128 v[24:27], v216 offset:39936
	v_lshl_add_u64 v[218:219], s[58:59], 0, v[196:197]
	s_mov_b32 m0, s63
	s_nop 0
	s_waitcnt vmcnt(4)
	s_barrier
	s_setprio 1
	v_mfma_f32_16x16x32_bf16 v[128:131], v[148:151], v[188:191], v[128:131]
	v_mfma_f32_16x16x32_bf16 v[124:127], v[156:159], v[188:191], v[124:127]
	v_mfma_f32_16x16x32_bf16 v[120:123], v[148:151], v[180:183], v[120:123]
	v_mfma_f32_16x16x32_bf16 v[116:119], v[156:159], v[180:183], v[116:119]
	v_mfma_f32_16x16x32_bf16 v[104:107], v[148:151], v[172:175], v[104:107]
	v_mfma_f32_16x16x32_bf16 v[100:103], v[156:159], v[172:175], v[100:103]
	v_mfma_f32_16x16x32_bf16 v[88:91], v[148:151], v[164:167], v[88:91]
	v_mfma_f32_16x16x32_bf16 v[84:87], v[156:159], v[164:167], v[84:87]
	v_mfma_f32_16x16x32_bf16 v[128:131], v[152:155], v[192:195], v[128:131]
	v_mfma_f32_16x16x32_bf16 v[124:127], v[160:163], v[192:195], v[124:127]
	v_mfma_f32_16x16x32_bf16 v[120:123], v[152:155], v[184:187], v[120:123]
	v_mfma_f32_16x16x32_bf16 v[116:119], v[160:163], v[184:187], v[116:119]
	v_mfma_f32_16x16x32_bf16 v[104:107], v[152:155], v[176:179], v[104:107]
	v_mfma_f32_16x16x32_bf16 v[100:103], v[160:163], v[176:179], v[100:103]
	v_mfma_f32_16x16x32_bf16 v[88:91], v[152:155], v[168:171], v[88:91]
	v_mfma_f32_16x16x32_bf16 v[84:87], v[160:163], v[168:171], v[84:87]
	s_setprio 0
	s_and_b64 vcc, exec, s[2:3]
	s_waitcnt lgkmcnt(0)
	s_barrier
	s_mov_b32 m0, s66
	v_lshl_add_u64 v[2:3], v[2:3], 0, s[16:17]
	s_add_u32 s56, s56, 0x80080
	global_load_lds_dwordx4 v[2:3], off
	v_lshl_add_u64 v[2:3], v[204:205], 0, s[16:17]
	s_mov_b32 m0, s67
	s_addc_u32 s57, s57, 0
	global_load_lds_dwordx4 v[2:3], off
	v_lshl_add_u64 v[2:3], s[56:57], 0, v[198:199]
	s_mov_b32 m0, s70
	s_and_b64 vcc, exec, s[2:3]
	v_lshl_add_u64 v[2:3], s[56:57], 0, v[196:197]
	s_mov_b32 m0, s71
	s_nop 0
	v_lshl_add_u64 v[2:3], v[206:207], 0, s[16:17]
	s_mov_b32 m0, s68
	s_nop 0
	global_load_lds_dwordx4 v[2:3], off
	v_lshl_add_u64 v[2:3], v[208:209], 0, s[16:17]
	s_mov_b32 m0, s69
	s_nop 0
	global_load_lds_dwordx4 v[2:3], off
	s_waitcnt vmcnt(4)
	s_waitcnt lgkmcnt(0)
	s_barrier
	s_branch .Lq5_be
.Lq5_exit:
	v_mfma_f32_16x16x32_bf16 v[128:131], v[4:7], v[44:47], v[128:131]
	v_mfma_f32_16x16x32_bf16 v[124:127], v[12:15], v[44:47], v[124:127]
	v_mfma_f32_16x16x32_bf16 v[120:123], v[4:7], v[36:39], v[120:123]
	v_mfma_f32_16x16x32_bf16 v[116:119], v[12:15], v[36:39], v[116:119]
	v_mfma_f32_16x16x32_bf16 v[104:107], v[4:7], v[28:31], v[104:107]
	v_mfma_f32_16x16x32_bf16 v[100:103], v[12:15], v[28:31], v[100:103]
	v_mfma_f32_16x16x32_bf16 v[88:91], v[4:7], v[20:23], v[88:91]
	v_mfma_f32_16x16x32_bf16 v[84:87], v[12:15], v[20:23], v[84:87]
	v_mfma_f32_16x16x32_bf16 v[128:131], v[8:11], v[48:51], v[128:131]
	v_mfma_f32_16x16x32_bf16 v[124:127], v[16:19], v[48:51], v[124:127]
	v_mfma_f32_16x16x32_bf16 v[120:123], v[8:11], v[40:43], v[120:123]
	v_mfma_f32_16x16x32_bf16 v[116:119], v[16:19], v[40:43], v[116:119]
	v_mfma_f32_16x16x32_bf16 v[104:107], v[8:11], v[32:35], v[104:107]
	v_mfma_f32_16x16x32_bf16 v[100:103], v[16:19], v[32:35], v[100:103]
	v_mfma_f32_16x16x32_bf16 v[88:91], v[8:11], v[24:27], v[88:91]
	v_mfma_f32_16x16x32_bf16 v[84:87], v[16:19], v[24:27], v[84:87]
	s_nop 7
	s_nop 1
	s_branch .LBB0_1140

.LBB0_1283:
	s_andn2_b64 vcc, exec, s[34:35]
	s_cbranch_vccnz .Lq6_entry
	ds_read_b128 v[180:183], v247
	ds_read_b128 v[184:187], v247 offset:1024
	ds_read_b128 v[188:191], v247 offset:2048
	ds_read_b128 v[192:195], v247 offset:3072
	ds_read_b128 v[164:167], v248
	ds_read_b128 v[168:171], v248 offset:1024
	ds_read_b128 v[172:175], v248 offset:2048
	ds_read_b128 v[176:179], v248 offset:3072
	v_lshl_add_u64 v[2:3], s[38:39], 0, v[232:233]
	s_add_i32 m0, s44, 0xc000
	ds_read_b128 v[220:223], v249
	ds_read_b128 v[224:227], v249 offset:1024
	ds_read_b128 v[212:215], v249 offset:2048
	ds_read_b128 v[216:219], v249 offset:3072
	ds_read_b128 v[204:207], v249 offset:4096
	ds_read_b128 v[208:211], v249 offset:5120
	ds_read_b128 v[196:199], v249 offset:6144
	ds_read_b128 v[200:203], v249 offset:7168
	global_load_lds_dwordx4 v[2:3], off
	v_lshl_add_u64 v[2:3], s[38:39], 0, v[234:235]
	s_add_i32 m0, s44, 0xe000
	s_nop 0
	global_load_lds_dwordx4 v[2:3], off
	s_waitcnt vmcnt(8)
	s_waitcnt lgkmcnt(0)
	s_barrier
	s_setprio 1
	s_waitcnt lgkmcnt(0)
	v_mfma_f32_16x16x32_bf16 v[68:71], v[180:183], v[220:223], v[160:163]
	v_mfma_f32_16x16x32_bf16 v[72:75], v[188:191], v[220:223], v[156:159]
	v_mfma_f32_16x16x32_bf16 v[76:79], v[180:183], v[212:215], v[152:155]
	v_mfma_f32_16x16x32_bf16 v[80:83], v[188:191], v[212:215], v[148:151]
	v_mfma_f32_16x16x32_bf16 v[84:87], v[180:183], v[204:207], v[136:139]
	v_mfma_f32_16x16x32_bf16 v[92:95], v[188:191], v[204:207], v[132:135]
	v_mfma_f32_16x16x32_bf16 v[96:99], v[180:183], v[196:199], v[120:123]
	v_mfma_f32_16x16x32_bf16 v[100:103], v[188:191], v[196:199], v[112:115]
	v_mfma_f32_16x16x32_bf16 v[68:71], v[184:187], v[224:227], v[68:71]
	v_mfma_f32_16x16x32_bf16 v[72:75], v[192:195], v[224:227], v[72:75]
	v_mfma_f32_16x16x32_bf16 v[76:79], v[184:187], v[216:219], v[76:79]
	v_mfma_f32_16x16x32_bf16 v[80:83], v[192:195], v[216:219], v[80:83]
	v_mfma_f32_16x16x32_bf16 v[84:87], v[184:187], v[208:211], v[84:87]
	v_mfma_f32_16x16x32_bf16 v[92:95], v[192:195], v[208:211], v[92:95]
	v_mfma_f32_16x16x32_bf16 v[96:99], v[184:187], v[200:203], v[96:99]
	v_mfma_f32_16x16x32_bf16 v[100:103], v[192:195], v[200:203], v[100:103]
	s_setprio 0
	v_cmp_ne_u32_e64 s[4:5], 1, v251
	s_andn2_b64 vcc, exec, s[34:35]
	s_cbranch_vccnz .LBB0_1285
	s_setprio 1
	v_mfma_f32_16x16x32_bf16 v[112:115], v[164:167], v[220:223], v[144:147]
	v_mfma_f32_16x16x32_bf16 v[144:147], v[168:171], v[224:227], v[112:115]
	v_mfma_f32_16x16x32_bf16 v[112:115], v[172:175], v[220:223], v[140:143]
	v_mfma_f32_16x16x32_bf16 v[140:143], v[176:179], v[224:227], v[112:115]
	v_mfma_f32_16x16x32_bf16 v[112:115], v[164:167], v[212:215], v[128:131]
	v_mfma_f32_16x16x32_bf16 v[128:131], v[168:171], v[216:219], v[112:115]
	v_mfma_f32_16x16x32_bf16 v[112:115], v[172:175], v[212:215], v[124:127]
	v_mfma_f32_16x16x32_bf16 v[124:127], v[176:179], v[216:219], v[112:115]
	v_mfma_f32_16x16x32_bf16 v[112:115], v[164:167], v[204:207], v[116:119]
	v_mfma_f32_16x16x32_bf16 v[108:111], v[172:175], v[204:207], v[108:111]
	v_mfma_f32_16x16x32_bf16 v[104:107], v[164:167], v[196:199], v[104:107]
	v_mfma_f32_16x16x32_bf16 v[88:91], v[172:175], v[196:199], v[88:91]
	v_mfma_f32_16x16x32_bf16 v[116:119], v[168:171], v[208:211], v[112:115]
	v_mfma_f32_16x16x32_bf16 v[108:111], v[176:179], v[208:211], v[108:111]
	v_mfma_f32_16x16x32_bf16 v[104:107], v[168:171], v[200:203], v[104:107]
	v_mfma_f32_16x16x32_bf16 v[88:91], v[176:179], v[200:203], v[88:91]
	s_setprio 0

.Lq6_top:
	ds_read_b128 v[180:183], v247
	ds_read_b128 v[184:187], v247 offset:1024
	ds_read_b128 v[188:191], v247 offset:2048
	ds_read_b128 v[192:195], v247 offset:3072
	v_lshl_add_u64 v[2:3], s[38:39], 0, v[232:233]
	s_add_i32 m0, s44, 0xc000
	ds_read_b128 v[220:223], v249
	ds_read_b128 v[224:227], v249 offset:1024
	ds_read_b128 v[212:215], v249 offset:2048
	ds_read_b128 v[216:219], v249 offset:3072
	ds_read_b128 v[204:207], v249 offset:4096
	ds_read_b128 v[208:211], v249 offset:5120
	ds_read_b128 v[196:199], v249 offset:6144
	ds_read_b128 v[200:203], v249 offset:7168
	v_lshl_add_u64 v[2:3], s[38:39], 0, v[234:235]
	s_add_i32 m0, s44, 0xe000
	s_nop 0
	s_waitcnt vmcnt(4)
	s_barrier
	s_setprio 1
	v_mfma_f32_16x16x32_bf16 v[68:71], v[4:7], v[44:47], v[160:163]
	v_mfma_f32_16x16x32_bf16 v[72:75], v[12:15], v[44:47], v[156:159]
	v_mfma_f32_16x16x32_bf16 v[76:79], v[4:7], v[36:39], v[152:155]
	v_mfma_f32_16x16x32_bf16 v[80:83], v[12:15], v[36:39], v[148:151]
	v_mfma_f32_16x16x32_bf16 v[84:87], v[4:7], v[28:31], v[136:139]
	v_mfma_f32_16x16x32_bf16 v[92:95], v[12:15], v[28:31], v[132:135]
	v_mfma_f32_16x16x32_bf16 v[96:99], v[4:7], v[20:23], v[120:123]
	v_mfma_f32_16x16x32_bf16 v[100:103], v[12:15], v[20:23], v[112:115]
	v_mfma_f32_16x16x32_bf16 v[68:71], v[8:11], v[48:51], v[68:71]
	v_mfma_f32_16x16x32_bf16 v[72:75], v[16:19], v[48:51], v[72:75]
	v_mfma_f32_16x16x32_bf16 v[76:79], v[8:11], v[40:43], v[76:79]
	v_mfma_f32_16x16x32_bf16 v[80:83], v[16:19], v[40:43], v[80:83]
	v_mfma_f32_16x16x32_bf16 v[84:87], v[8:11], v[32:35], v[84:87]
	v_mfma_f32_16x16x32_bf16 v[92:95], v[16:19], v[32:35], v[92:95]
	v_mfma_f32_16x16x32_bf16 v[96:99], v[8:11], v[24:27], v[96:99]
	v_mfma_f32_16x16x32_bf16 v[100:103], v[16:19], v[24:27], v[100:103]
	s_setprio 0
	v_cmp_ne_u32_e64 s[4:5], 1, v251
	s_andn2_b64 vcc, exec, s[34:35]
	s_add_u32 s40, s38, 0xfff80080
	s_addc_u32 s41, s39, -1
	s_cmp_eq_u32 s84, 28
	s_cselect_b32 s47, s29, s41
	s_cselect_b32 s46, s28, s40
	s_cselect_b32 s41, s37, s27
	s_cselect_b32 s40, s36, s16
	s_waitcnt lgkmcnt(0)
	s_barrier
	s_mov_b32 m0, s45
	v_lshl_add_u64 v[2:3], s[40:41], 0, v[230:231]
	s_add_u32 s86, s40, 0x80000
	global_load_lds_dwordx4 v[2:3], off
	v_lshl_add_u64 v[236:237], s[40:41], 0, v[228:229]
	s_mov_b32 m0, s48
	s_addc_u32 s87, s41, 0
	global_load_lds_dwordx4 v[236:237], off
	v_lshl_add_u64 v[54:55], s[86:87], 0, v[230:231]
	s_mov_b32 m0, s49
	v_lshl_add_u64 v[238:239], s[46:47], 0, v[230:231]
	v_lshl_add_u64 v[54:55], s[86:87], 0, v[228:229]
	s_mov_b32 m0, s50
	v_lshl_add_u64 v[240:241], s[46:47], 0, v[228:229]
	s_mov_b32 m0, s44
	s_and_b64 vcc, exec, s[4:5]
	global_load_lds_dwordx4 v[238:239], off
	s_mov_b32 m0, s51
	s_nop 0
	global_load_lds_dwordx4 v[240:241], off
	s_waitcnt vmcnt(4)
	s_waitcnt lgkmcnt(0)
	s_barrier
	s_barrier
	v_add_u32_e32 v1, 0x18000, v246
	ds_read_b128 v[4:7], v1
	ds_read_b128 v[8:11], v1 offset:1024
	ds_read_b128 v[12:15], v1 offset:2048
	ds_read_b128 v[16:19], v1 offset:3072
	v_add_u32_e32 v1, 0x1c000, v246
	s_add_u32 s46, s46, 0x80000
	s_addc_u32 s47, s47, 0
	s_mov_b32 m0, s56
	v_lshl_add_u64 v[112:113], s[46:47], 0, v[230:231]
	ds_read_b128 v[44:47], v249 offset:32768
	ds_read_b128 v[48:51], v249 offset:33792
	ds_read_b128 v[36:39], v249 offset:34816
	ds_read_b128 v[40:43], v249 offset:35840
	ds_read_b128 v[28:31], v249 offset:36864
	ds_read_b128 v[32:35], v249 offset:37888
	ds_read_b128 v[20:23], v249 offset:38912
	ds_read_b128 v[24:27], v249 offset:39936
	v_lshl_add_u64 v[112:113], s[46:47], 0, v[228:229]
	s_mov_b32 m0, s57
	s_nop 0
	s_waitcnt vmcnt(4)
	s_barrier
	s_setprio 1
	v_mfma_f32_16x16x32_bf16 v[68:71], v[180:183], v[220:223], v[68:71]
	v_mfma_f32_16x16x32_bf16 v[160:163], v[184:187], v[224:227], v[68:71]
	v_mfma_f32_16x16x32_bf16 v[68:71], v[188:191], v[220:223], v[72:75]
	v_mfma_f32_16x16x32_bf16 v[156:159], v[192:195], v[224:227], v[68:71]
	v_mfma_f32_16x16x32_bf16 v[68:71], v[180:183], v[212:215], v[76:79]
	v_mfma_f32_16x16x32_bf16 v[152:155], v[184:187], v[216:219], v[68:71]
	v_mfma_f32_16x16x32_bf16 v[68:71], v[188:191], v[212:215], v[80:83]
	v_mfma_f32_16x16x32_bf16 v[148:151], v[192:195], v[216:219], v[68:71]
	v_mfma_f32_16x16x32_bf16 v[68:71], v[180:183], v[204:207], v[84:87]
	v_mfma_f32_16x16x32_bf16 v[136:139], v[184:187], v[208:211], v[68:71]
	v_mfma_f32_16x16x32_bf16 v[68:71], v[188:191], v[204:207], v[92:95]
	v_mfma_f32_16x16x32_bf16 v[132:135], v[192:195], v[208:211], v[68:71]
	v_mfma_f32_16x16x32_bf16 v[68:71], v[180:183], v[196:199], v[96:99]
	v_mfma_f32_16x16x32_bf16 v[120:123], v[184:187], v[200:203], v[68:71]
	v_mfma_f32_16x16x32_bf16 v[68:71], v[188:191], v[196:199], v[100:103]
	v_mfma_f32_16x16x32_bf16 v[112:115], v[192:195], v[200:203], v[68:71]
	s_setprio 0
	s_and_b64 vcc, exec, s[4:5]
	s_waitcnt lgkmcnt(0)
	s_barrier
	s_mov_b32 m0, s61
	v_lshl_add_u64 v[2:3], v[2:3], 0, s[14:15]
	s_add_u32 s40, s40, 0x80080
	global_load_lds_dwordx4 v[2:3], off
	v_lshl_add_u64 v[2:3], v[236:237], 0, s[14:15]
	s_mov_b32 m0, s62
	s_addc_u32 s41, s41, 0
	global_load_lds_dwordx4 v[2:3], off
	v_lshl_add_u64 v[2:3], s[40:41], 0, v[230:231]
	s_mov_b32 m0, s65
	s_and_b64 vcc, exec, s[4:5]
	v_lshl_add_u64 v[2:3], s[40:41], 0, v[228:229]
	s_mov_b32 m0, s66
	s_nop 0
	v_lshl_add_u64 v[2:3], v[238:239], 0, s[14:15]
	s_mov_b32 m0, s63
	s_nop 0
	global_load_lds_dwordx4 v[2:3], off
	v_lshl_add_u64 v[2:3], v[240:241], 0, s[14:15]
	s_mov_b32 m0, s64
	s_nop 0
	global_load_lds_dwordx4 v[2:3], off
	s_waitcnt vmcnt(4)
	s_waitcnt lgkmcnt(0)
	s_barrier
	s_branch .Lq6_be
.Lq6_exit:
	v_mfma_f32_16x16x32_bf16 v[160:163], v[4:7], v[44:47], v[160:163]
	v_mfma_f32_16x16x32_bf16 v[156:159], v[12:15], v[44:47], v[156:159]
	v_mfma_f32_16x16x32_bf16 v[152:155], v[4:7], v[36:39], v[152:155]
	v_mfma_f32_16x16x32_bf16 v[148:151], v[12:15], v[36:39], v[148:151]
	v_mfma_f32_16x16x32_bf16 v[136:139], v[4:7], v[28:31], v[136:139]
	v_mfma_f32_16x16x32_bf16 v[132:135], v[12:15], v[28:31], v[132:135]
	v_mfma_f32_16x16x32_bf16 v[120:123], v[4:7], v[20:23], v[120:123]
	v_mfma_f32_16x16x32_bf16 v[112:115], v[12:15], v[20:23], v[112:115]
	v_mfma_f32_16x16x32_bf16 v[160:163], v[8:11], v[48:51], v[160:163]
	v_mfma_f32_16x16x32_bf16 v[156:159], v[16:19], v[48:51], v[156:159]
	v_mfma_f32_16x16x32_bf16 v[152:155], v[8:11], v[40:43], v[152:155]
	v_mfma_f32_16x16x32_bf16 v[148:151], v[16:19], v[40:43], v[148:151]
	v_mfma_f32_16x16x32_bf16 v[136:139], v[8:11], v[32:35], v[136:139]
	v_mfma_f32_16x16x32_bf16 v[132:135], v[16:19], v[32:35], v[132:135]
	v_mfma_f32_16x16x32_bf16 v[120:123], v[8:11], v[24:27], v[120:123]
	v_mfma_f32_16x16x32_bf16 v[112:115], v[16:19], v[24:27], v[112:115]
	s_nop 7
	s_nop 1
	s_branch .LBB0_1291
